# P3 rebalance: pool blocks take 4 pool items + 1 sample item, sample blocks 3 sample items
# speedup vs baseline: 1.0172x; 1.0172x over previous
; __global__ void __launch_bounds__(512, 2) fwd_megakernel(Args a) {
;     ...
;         for (int it = bid; it < 512; it += G) { const int x = it & 7, loc = it >> 3, bh = x * 16 + (loc >> 2); mlstm_item(a, L, true, bh >> 2, bh & 3, loc & 3); }
.LBB0_707:
	s_and_b32 s98, s2, 31
	s_lshr_b32 s99, s2, 6
	s_lshl_b32 s99, s99, 5
	s_or_b32 s98, s98, s99
	s_movk_i32 s99, 0x80
	s_movk_i32 s100, 0x17f
	s_bitcmp1_b32 s2, 5
	s_cbranch_scc0 .Lsm_go
	s_addk_i32 s98, 0x180
	s_movk_i32 s100, 0x1ff
.Lsm_go:
	s_add_u32 s33, s26, 0x96e0100
	s_addc_u32 s56, s27, 0
	s_add_u32 s57, s26, 0xb6e0100
	s_addc_u32 s58, s27, 0
	s_add_u32 s59, s26, 0xb700100
	s_addc_u32 s64, s27, 0
	s_lshl_b32 s65, s98, 4
	s_lshl_b32 s68, s99, 4
	s_mov_b32 s11, 0
	v_mov_b32_e32 v41, 0
	v_mov_b32_e32 v86, 0x3f80
	s_movk_i32 s69, 0x50
	s_movk_i32 s70, 0x210
	s_movk_i32 s71, 0x3800
	s_movk_i32 s72, 0x100
	s_movk_i32 s73, 0x3000
	s_mov_b32 s76, 0xbfb8aa3b
	s_mov_b32 s77, 0x3f2aaaab
	v_mov_b32_e32 v87, 0x3ecc95a3
	s_mov_b32 s78, 0x3f317218
	s_mov_b32 s79, 0x7f800000
	s_mov_b32 s80, 0x33800000
	v_mov_b32_e32 v88, 0xff800000
	s_add_i32 s81, 0, 0x1e700
	s_movk_i32 s82, 0xfe1f
	s_mov_b32 s83, 0xffff
	s_movk_i32 s84, 0x140
	s_movk_i32 s85, 0x20c
	s_mov_b32 s86, 0xc000
	s_movk_i32 s87, 0xfe40
	s_movk_i32 s88, 0x1c0
	v_mov_b32_e32 v89, 0x4200
	v_mov_b32_e32 v90, 0x6300
	v_mov_b32_e32 v91, 0x7f800000
	v_mov_b32_e32 v92, 0x7fc00000
	v_mbcnt_hi_u32_b32 v93, -1, v181
	s_mov_b32 s89, s98
	s_branch .LBB0_710
.LBB0_709:
	s_or_b64 exec, exec, s[0:1]
	s_waitcnt lgkmcnt(0)
	s_barrier
	s_add_i32 s89, s89, s99
	s_add_i32 s65, s65, s68
	s_cmp_gt_i32 s89, s100
	s_cbranch_scc1 .LBB0_775
